# attention: barrier moved to the QK/PV boundary (4-deep V ring), next tile's first K fragments requested before the softmax tail, first V fragments requested before the barrier
# baseline (speedup 1.0000x reference)
.LBB0_725:
	s_ashr_i32 s42, s4, 8
	s_ashr_i32 s43, s42, 31
	s_lshl_b32 s10, s4, 8
	s_lshl_b64 s[46:47], s[42:43], 13
	s_and_b32 s10, s10, 0x1f00
	s_or_b32 s46, s46, s10
	s_lshl_b32 s2, s4, 1
	s_mul_i32 s10, s47, 0xc00
	s_mul_hi_u32 s11, s46, 0xc00
	s_and_b32 s2, s2, 0x100
	s_bfe_u32 s3, s4, 0x30005
	s_add_i32 s11, s11, s10
	s_mul_i32 s10, s46, 0xc00
	s_add_u32 s16, s6, s10
	s_addc_u32 s11, s7, s11
	s_lshl_b32 s10, s3, 7
	s_lshl_b32 s3, s3, 8
	s_add_u32 s18, s16, s3
	s_addc_u32 s19, s11, 0
	s_mul_i32 s11, s42, 0x1800000
	s_mul_hi_i32 s3, s42, 0x1800000
	s_add_u32 s11, s6, s11
	s_addc_u32 s3, s7, s3
	s_and_b32 s16, s4, 0x80
	s_lshl_b32 s16, s16, 1
	s_add_u32 s40, s11, s16
	v_mov_b32_e32 v48, v192
	s_addc_u32 s41, s3, 0
	s_barrier
	s_add_i32 s3, 0, 0x10000
	v_and_b32_e32 v0, 0x3fffffc0, v48
	v_lshl_add_u32 v177, v0, 2, s3
	v_ashrrev_i32_e32 v0, 1, v48
	s_movk_i32 s3, 0xffe0
	v_bfe_u32 v181, v48, 5, 1
	v_and_b32_e32 v176, 0xffffffe0, v0
	v_bfi_b32 v2, s3, v0, v48
	v_mov_b64_e32 v[0:1], s[18:19]
	s_movk_i32 s20, 0xc00
	v_mad_i64_i32 v[0:1], s[18:19], v2, s20, v[0:1]
	v_lshlrev_b32_e32 v194, 4, v181
	v_lshl_add_u64 v[0:1], v[0:1], 0, v[194:195]
	v_ashrrev_i32_e32 v50, 4, v48
	global_load_dwordx4 v[124:127], v[0:1], off
	global_load_dwordx4 v[120:123], v[0:1], off offset:32
	global_load_dwordx4 v[116:119], v[0:1], off offset:64
	global_load_dwordx4 v[112:115], v[0:1], off offset:96
	global_load_dwordx4 v[108:111], v[0:1], off offset:128
	global_load_dwordx4 v[104:107], v[0:1], off offset:160
	global_load_dwordx4 v[100:103], v[0:1], off offset:192
	global_load_dwordx4 v[96:99], v[0:1], off offset:224
	v_and_b32_e32 v1, 0xfffff0, v50
	v_lshlrev_b32_e32 v2, 1, v50
	v_lshlrev_b32_e32 v0, 3, v48
	v_and_or_b32 v1, v2, 8, v1
	v_and_b32_e32 v52, 0x78, v0
	v_lshrrev_b32_e32 v2, 1, v50
	v_lshrrev_b32_e32 v1, 1, v1
	v_bfe_u32 v0, v0, 5, 2
	v_and_b32_e32 v3, 3, v50
	v_or_b32_e32 v1, v1, v0
	v_and_or_b32 v2, v2, 4, v3
	v_lshlrev_b32_e32 v16, 1, v52
	v_lshlrev_b32_e32 v1, 9, v1
	v_lshlrev_b32_e32 v2, 6, v2
	v_and_b32_e32 v3, 48, v16
	v_add_u32_e32 v18, 32, v50
	v_or3_b32 v17, v1, v2, v3
	v_and_b32_e32 v1, 0xfffff0, v18
	v_lshlrev_b32_e32 v4, 1, v18
	v_and_or_b32 v1, v4, 8, v1
	v_lshrrev_b32_e32 v1, 1, v1
	v_or_b32_e32 v0, v1, v0
	v_and_b32_e32 v49, 63, v48
	v_lshlrev_b32_e32 v0, 9, v0
	v_lshlrev_b32_e32 v20, 4, v48
	v_or3_b32 v19, v0, v2, v3
	v_lshlrev_b32_e32 v0, 3, v49
	v_and_b32_e32 v1, 0xc0, v20
	v_lshlrev_b32_e32 v2, 1, v48
	v_and_or_b32 v1, v0, 24, v1
	v_and_b32_e32 v2, 32, v2
	v_and_b32_e32 v0, 0x100, v0
	s_movk_i32 s16, 0x600
	v_or3_b32 v51, v1, v2, v0
	v_mad_i64_i32 v[0:1], s[18:19], v50, s16, 0
	v_or_b32_e32 v0, v0, v52
	v_lshl_add_u64 v[8:9], v[0:1], 1, s[40:41]
	global_load_dwordx4 v[0:3], v[8:9], off offset:2560
	v_mad_i64_i32 v[4:5], s[18:19], v18, s16, 0
	v_or_b32_e32 v4, v4, v52
	v_lshl_add_u64 v[12:13], v[4:5], 1, s[40:41]
	global_load_dwordx4 v[4:7], v[12:13], off offset:2560
	s_nop 0
	global_load_dwordx4 v[8:11], v[8:9], off offset:2048
	s_nop 0
	global_load_dwordx4 v[12:15], v[12:13], off offset:2048
	v_add_u32_e32 v183, 0, v17
	s_waitcnt vmcnt(0)
	v_and_b32_e32 v180, 31, v48
	v_lshlrev_b32_e32 v53, 8, v180
	v_and_b32_e32 v62, 0x70, v20
	v_add_u32_e32 v184, 0, v19
	v_or_b32_e32 v54, 32, v194
	v_bitop3_b32 v54, v54, v53, v62 bitop3:0xde
	v_add_u32_e32 v205, 0, v54
	s_cmp_lg_u32 0, -1
	s_cselect_b32 s3, 0, 0
	s_mov_b32 s53, s52
	s_mov_b32 s54, s52
	s_mov_b32 s55, s52
	s_mov_b32 s56, s52
	s_mov_b32 s57, s52
	s_mov_b32 s58, s52
	s_mov_b32 s59, s52
	s_mov_b32 s60, s52
	s_mov_b32 s61, s52
	s_mov_b32 s62, s52
	s_mov_b32 s63, s52
	s_mov_b32 s64, s52
	s_mov_b32 s65, s52
	s_mov_b32 s66, s52
	s_mov_b32 s67, s52
	v_add_u32_e32 v182, s3, v51
	s_mov_b32 s11, -1
	v_lshl_add_u32 v185, v180, 2, v177
	s_movk_i32 s15, 0xc00
	v_mov_b32_e32 v186, 0
	s_waitcnt vmcnt(3)
	ds_write_b128 v183, v[0:3]
	v_lshlrev_b32_e32 v0, 8, v50
	v_and_b32_e32 v1, 0x70, v48
	v_bitop3_b32 v0, v16, v0, v1 bitop3:0xde
	v_add_u32_e32 v188, 0, v0
	v_lshlrev_b32_e32 v0, 8, v18
	v_bitop3_b32 v0, v16, v0, v1 bitop3:0xde
	v_add_u32_e32 v189, 0, v0
	v_bitop3_b32 v0, v194, v53, v62 bitop3:0xde
	v_add_u32_e32 v190, 0, v0
	s_waitcnt vmcnt(2)
	ds_write_b128 v184, v[4:7]
	s_waitcnt vmcnt(1)
	ds_write_b128 v188, v[8:11] offset:32768
	s_waitcnt vmcnt(0)
	ds_write_b128 v189, v[12:15] offset:32768
	s_waitcnt lgkmcnt(0)
	s_barrier
	ds_read_b128 v[16:19], v190 offset:32768
	ds_read_b128 v[20:23], v190 offset:40960
	s_waitcnt lgkmcnt(1)
	v_mfma_f32_32x32x16_bf16 v[32:47], v[16:19], v[124:127], 0
	ds_read_b128 v[54:57], v205 offset:32768
	ds_read_b128 v[58:61], v205 offset:40960
	v_mov_b64_e32 v[0:1], s[52:53]
	v_mov_b64_e32 v[14:15], s[66:67]
	v_mov_b64_e32 v[2:3], s[54:55]
	v_mov_b64_e32 v[4:5], s[56:57]
	v_mov_b64_e32 v[6:7], s[58:59]
	v_mov_b64_e32 v[8:9], s[60:61]
	s_waitcnt lgkmcnt(2)
	v_mfma_f32_32x32x16_bf16 v[16:31], v[20:23], v[124:127], 0
	v_mov_b64_e32 v[10:11], s[62:63]
	v_mov_b64_e32 v[12:13], s[64:65]
	s_waitcnt lgkmcnt(1)
	v_mfma_f32_32x32x16_bf16 v[32:47], v[54:57], v[120:123], v[32:47]
	v_or_b32_e32 v54, 64, v194
	v_bitop3_b32 v54, v54, v53, v62 bitop3:0xde
	v_add_u32_e32 v204, 0, v54
	s_waitcnt lgkmcnt(0)
	v_mfma_f32_32x32x16_bf16 v[16:31], v[58:61], v[120:123], v[16:31]
	ds_read_b128 v[54:57], v204 offset:32768
	ds_read_b128 v[58:61], v204 offset:40960
	s_waitcnt lgkmcnt(1)
	v_mfma_f32_32x32x16_bf16 v[32:47], v[54:57], v[116:119], v[32:47]
	v_or_b32_e32 v54, 0x60, v194
	v_bitop3_b32 v54, v54, v53, v62 bitop3:0xde
	v_add_u32_e32 v202, 0, v54
	s_waitcnt lgkmcnt(0)
	v_mfma_f32_32x32x16_bf16 v[16:31], v[58:61], v[116:119], v[16:31]
	ds_read_b128 v[54:57], v202 offset:32768
	ds_read_b128 v[58:61], v202 offset:40960
	s_waitcnt lgkmcnt(1)
	v_mfma_f32_32x32x16_bf16 v[32:47], v[54:57], v[112:115], v[32:47]
	v_or_b32_e32 v54, 0x80, v194
	v_bitop3_b32 v54, v54, v53, v62 bitop3:0xde
	v_add_u32_e32 v191, 0, v54
	s_waitcnt lgkmcnt(0)
	v_mfma_f32_32x32x16_bf16 v[16:31], v[58:61], v[112:115], v[16:31]
	ds_read_b128 v[54:57], v191 offset:32768
	ds_read_b128 v[58:61], v191 offset:40960
	s_waitcnt lgkmcnt(1)
	v_mfma_f32_32x32x16_bf16 v[32:47], v[54:57], v[108:111], v[32:47]
	v_or_b32_e32 v54, 0xa0, v194
	v_bitop3_b32 v54, v54, v53, v62 bitop3:0xde
	v_add_u32_e32 v203, 0, v54
	s_waitcnt lgkmcnt(0)
	v_mfma_f32_32x32x16_bf16 v[16:31], v[58:61], v[108:111], v[16:31]
	ds_read_b128 v[54:57], v203 offset:32768
	ds_read_b128 v[58:61], v203 offset:40960
	s_waitcnt lgkmcnt(1)
	v_mfma_f32_32x32x16_bf16 v[32:47], v[54:57], v[104:107], v[32:47]
	v_or_b32_e32 v54, 0xc0, v194
	v_bitop3_b32 v54, v54, v53, v62 bitop3:0xde
	v_add_u32_e32 v206, 0, v54
	s_waitcnt lgkmcnt(0)
	v_mfma_f32_32x32x16_bf16 v[16:31], v[58:61], v[104:107], v[16:31]
	ds_read_b128 v[54:57], v206 offset:32768
	ds_read_b128 v[58:61], v206 offset:40960
	s_waitcnt lgkmcnt(1)
	v_mfma_f32_32x32x16_bf16 v[32:47], v[54:57], v[100:103], v[32:47]
	v_or_b32_e32 v54, 0xe0, v194
	v_bitop3_b32 v53, v54, v53, v62 bitop3:0xde
	v_add_u32_e32 v207, 0, v53
	s_waitcnt lgkmcnt(0)
	v_mfma_f32_32x32x16_bf16 v[16:31], v[58:61], v[100:103], v[16:31]
	ds_read_b128 v[54:57], v207 offset:32768
	ds_read_b128 v[58:61], v207 offset:40960
	s_waitcnt lgkmcnt(1)
	v_mfma_f32_32x32x16_bf16 v[32:47], v[54:57], v[96:99], v[32:47]
	v_mov_b32_e32 v55, 0xf149f2ca
	s_waitcnt lgkmcnt(0)
	v_mfma_f32_32x32x16_bf16 v[16:31], v[58:61], v[96:99], v[16:31]
	s_nop 8
	v_max_f32_e32 v53, v33, v33
	v_max_f32_e32 v54, v32, v32
	v_max_f32_e32 v53, v54, v53
	v_max3_f32 v53, v53, v34, v35
	v_max3_f32 v53, v53, v36, v37
	v_max3_f32 v53, v53, v38, v39
	v_max3_f32 v53, v53, v40, v41
	v_max3_f32 v53, v53, v42, v43
	v_max3_f32 v53, v53, v44, v45
	v_max3_f32 v53, v53, v46, v47
	v_max3_f32 v53, v53, v16, v17
	v_max3_f32 v53, v53, v18, v19
	v_max3_f32 v53, v53, v20, v21
	v_max3_f32 v53, v53, v22, v23
	v_max3_f32 v53, v53, v24, v25
	v_max3_f32 v53, v53, v26, v27
	v_max3_f32 v53, v53, v28, v29
	v_max3_f32 v53, v53, v30, v31
	v_mov_b32_e32 v54, v53
	s_nop 1
	v_permlane32_swap_b32_e32 v53, v54
	v_max_f32_e32 v54, v54, v54
	v_max_f32_e32 v53, v53, v53
	v_max_f32_e32 v53, v53, v54
	v_add_f32_e32 v54, 0x7149f2ca, v53
	v_max_f32_e32 v53, 0xf149f2ca, v53
	v_cmp_ge_f32_e32 vcc, s85, v54
	v_sub_f32_e32 v54, 0xf149f2ca, v53
	v_mul_f32_e32 v54, 0x3e0293ee, v54
	v_exp_f32_e32 v54, v54
	s_cmp_eq_u64 vcc, exec
	s_cselect_b64 vcc, -1, 0
	v_cndmask_b32_e32 v164, v53, v55, vcc
	v_cndmask_b32_e64 v208, v54, 1.0, vcc
	v_mul_f32_e32 v54, 0xbe0293ee, v164
	v_pk_fma_f32 v[148:149], v[20:21], s[12:13], v[54:55] op_sel_hi:[1,0,0]
	v_pk_fma_f32 v[156:157], v[16:17], s[12:13], v[54:55] op_sel_hi:[1,0,0]
	v_add_u32_e32 v16, 64, v50
	v_add_u32_e32 v20, 0x60, v50
	v_mad_i64_i32 v[16:17], s[18:19], v16, s16, 0
	v_mad_i64_i32 v[20:21], s[18:19], v20, s16, 0
	v_or_b32_e32 v16, v16, v52
	v_or_b32_e32 v20, v20, v52
	v_pk_fma_f32 v[152:153], v[28:29], s[12:13], v[54:55] op_sel_hi:[1,0,0]
	v_pk_fma_f32 v[144:145], v[24:25], s[12:13], v[54:55] op_sel_hi:[1,0,0]
	v_lshl_add_u64 v[24:25], v[16:17], 1, s[40:41]
	v_lshl_add_u64 v[28:29], v[20:21], 1, s[40:41]
	v_fmamk_f32 v32, v32, 0x3e0293ee, v54
	v_fmamk_f32 v34, v34, 0x3e0293ee, v54
	v_pk_fma_f32 v[150:151], v[30:31], s[12:13], v[54:55] op_sel_hi:[1,0,0]
	v_pk_fma_f32 v[158:159], v[26:27], s[12:13], v[54:55] op_sel_hi:[1,0,0]
	v_pk_fma_f32 v[146:147], v[22:23], s[12:13], v[54:55] op_sel_hi:[1,0,0]
	v_pk_fma_f32 v[154:155], v[18:19], s[12:13], v[54:55] op_sel_hi:[1,0,0]
	global_load_dwordx4 v[16:19], v[24:25], off offset:2560
	global_load_dwordx4 v[20:23], v[28:29], off offset:2560
	s_nop 0
	global_load_dwordx4 v[24:27], v[24:25], off offset:2048
	s_nop 0
	global_load_dwordx4 v[28:31], v[28:29], off offset:2048
	v_fmamk_f32 v33, v33, 0x3e0293ee, v54
	v_fmamk_f32 v35, v35, 0x3e0293ee, v54
	v_exp_f32_e32 v238, v32
	v_exp_f32_e32 v240, v34
	v_add_u32_e32 v32, 0x80, v50
	v_add_u32_e32 v34, 0xa0, v50
	v_exp_f32_e32 v239, v33
	v_exp_f32_e32 v246, v35
	v_mad_i64_i32 v[32:33], s[18:19], v32, s16, 0
	v_mad_i64_i32 v[34:35], s[18:19], v34, s16, 0
	v_or_b32_e32 v32, v32, v52
	v_or_b32_e32 v34, v34, v52
	v_lshl_add_u64 v[32:33], v[32:33], 1, s[40:41]
	v_lshl_add_u64 v[34:35], v[34:35], 1, s[40:41]
	global_load_dwordx4 v[128:131], v[32:33], off offset:2560
	global_load_dwordx4 v[132:135], v[34:35], off offset:2560
	global_load_dwordx4 v[136:139], v[32:33], off offset:2048
	global_load_dwordx4 v[140:143], v[34:35], off offset:2048
	v_mov_b32_e32 v53, v54
	s_waitcnt vmcnt(4)
	s_waitcnt vmcnt(7)
	ds_write_b128 v183, v[16:19] offset:16384
	s_waitcnt vmcnt(6)
	ds_write_b128 v184, v[20:23] offset:16384
	s_waitcnt vmcnt(5)
	ds_write_b128 v188, v[24:27] offset:49152
	s_waitcnt vmcnt(4)
	ds_write_b128 v189, v[28:31] offset:49152
	v_mad_i64_i32 v[16:17], s[18:19], v50, s20, 0
	v_mov_b32_e32 v18, 0x1800000
	v_fmamk_f32 v36, v36, 0x3e0293ee, v54
	v_fmamk_f32 v37, v37, 0x3e0293ee, v54
	v_fmamk_f32 v38, v38, 0x3e0293ee, v54
	v_fmamk_f32 v39, v39, 0x3e0293ee, v54
	v_fmamk_f32 v40, v40, 0x3e0293ee, v54
	v_fmamk_f32 v41, v41, 0x3e0293ee, v54
	v_fmamk_f32 v42, v42, 0x3e0293ee, v54
	v_fmamk_f32 v43, v43, 0x3e0293ee, v54
	v_fmamk_f32 v44, v44, 0x3e0293ee, v54
	v_fmamk_f32 v45, v45, 0x3e0293ee, v54
	v_fmamk_f32 v46, v46, 0x3e0293ee, v54
	v_fmac_f32_e32 v53, 0x3e0293ee, v47
	v_mad_i64_i32 v[16:17], s[18:19], s42, v18, v[16:17]
	v_and_b32_e32 v18, 15, v48
	v_exp_f32_e32 v247, v36
	v_exp_f32_e32 v248, v37
	v_exp_f32_e32 v249, v38
	v_exp_f32_e32 v250, v39
	v_exp_f32_e32 v251, v40
	v_exp_f32_e32 v252, v41
	v_exp_f32_e32 v253, v42
	v_exp_f32_e32 v241, v43
	v_exp_f32_e32 v243, v44
	v_exp_f32_e32 v244, v45
	v_exp_f32_e32 v245, v46
	v_exp_f32_e32 v193, v53
	v_lshlrev_b32_e32 v18, 4, v18
	s_addk_i32 s3, 0x4000
	v_or3_b32 v16, v16, s2, v18
	v_cmp_gt_u32_e64 s[40:41], 32, v49
	v_add_u32_e32 v187, s3, v51
	v_lshl_add_u64 v[178:179], s[44:45], 0, v[16:17]
	v_mov_b64_e32 v[62:63], v[14:15]
	v_mov_b64_e32 v[46:47], v[14:15]
	v_mov_b64_e32 v[30:31], v[14:15]
	v_mov_b64_e32 v[60:61], v[12:13]
	v_mov_b64_e32 v[58:59], v[10:11]
	v_mov_b64_e32 v[56:57], v[8:9]
	v_mov_b64_e32 v[54:55], v[6:7]
	v_mov_b64_e32 v[52:53], v[4:5]
	v_mov_b64_e32 v[50:51], v[2:3]
	v_mov_b64_e32 v[48:49], v[0:1]
	v_mov_b64_e32 v[44:45], v[12:13]
	v_mov_b64_e32 v[42:43], v[10:11]
	v_mov_b64_e32 v[40:41], v[8:9]
	v_mov_b64_e32 v[38:39], v[6:7]
	v_mov_b64_e32 v[36:37], v[4:5]
	v_mov_b64_e32 v[34:35], v[2:3]
	v_mov_b64_e32 v[32:33], v[0:1]
	v_mov_b64_e32 v[28:29], v[12:13]
	v_mov_b64_e32 v[26:27], v[10:11]
	v_mov_b64_e32 v[24:25], v[8:9]
	v_mov_b64_e32 v[22:23], v[6:7]
	v_mov_b64_e32 v[20:21], v[4:5]
	v_mov_b64_e32 v[18:19], v[2:3]
	v_mov_b64_e32 v[16:17], v[0:1]
	s_waitcnt lgkmcnt(0)
	s_barrier
	s_mov_b32 s90, 0
	s_movk_i32 s91, 0x4000
	s_mov_b32 s92, 0x10800
	s_mov_b32 s99, 0x14800
	ds_read_b128 v[214:217], v190 offset:49152
	ds_read_b128 v[218:221], v190 offset:57344
	ds_read_b128 v[222:225], v205 offset:49152
	ds_read_b128 v[226:229], v205 offset:57344
.LBB0_726:
	v_exp_f32_e32 v156, v156
	v_exp_f32_e32 v157, v157
	v_add_f32_e32 v209, v238, v239
	s_waitcnt lgkmcnt(3)
	v_mfma_f32_32x32x16_bf16 v[80:95], v[214:217], v[124:127], 0
	v_exp_f32_e32 v154, v154
	v_exp_f32_e32 v155, v155
	v_add_f32_e32 v209, v240, v209
	v_add_f32_e32 v209, v246, v209
	s_waitcnt lgkmcnt(2)
	v_mfma_f32_32x32x16_bf16 v[64:79], v[218:221], v[124:127], 0
	ds_read_b128 v[214:217], v204 offset:49152
	ds_read_b128 v[218:221], v204 offset:57344
	v_exp_f32_e32 v148, v148
	v_exp_f32_e32 v149, v149
	v_add_f32_e32 v209, v247, v209
	v_add_f32_e32 v209, v248, v209
	s_waitcnt lgkmcnt(3)
	v_mfma_f32_32x32x16_bf16 v[80:95], v[222:225], v[120:123], v[80:95]
	v_exp_f32_e32 v146, v146
	v_exp_f32_e32 v147, v147
	v_add_f32_e32 v209, v249, v209
	v_add_f32_e32 v209, v250, v209
	s_waitcnt lgkmcnt(2)
	v_mfma_f32_32x32x16_bf16 v[64:79], v[226:229], v[120:123], v[64:79]
	ds_read_b128 v[222:225], v202 offset:49152
	ds_read_b128 v[226:229], v202 offset:57344
	v_exp_f32_e32 v144, v144
	v_exp_f32_e32 v145, v145
	v_add_f32_e32 v209, v251, v209
	v_add_f32_e32 v209, v252, v209
	s_waitcnt lgkmcnt(3)
	v_mfma_f32_32x32x16_bf16 v[80:95], v[214:217], v[116:119], v[80:95]
	v_exp_f32_e32 v158, v158
	v_exp_f32_e32 v159, v159
	v_add_f32_e32 v209, v253, v209
	v_add_f32_e32 v209, v241, v209
	s_waitcnt lgkmcnt(2)
	v_mfma_f32_32x32x16_bf16 v[64:79], v[218:221], v[116:119], v[64:79]
	ds_read_b128 v[214:217], v191 offset:49152
	ds_read_b128 v[218:221], v191 offset:57344
	v_exp_f32_e32 v152, v152
	v_exp_f32_e32 v153, v153
	v_add_f32_e32 v209, v243, v209
	v_add_f32_e32 v209, v244, v209
	s_waitcnt lgkmcnt(3)
	v_mfma_f32_32x32x16_bf16 v[80:95], v[222:225], v[112:115], v[80:95]
	v_exp_f32_e32 v150, v150
	v_exp_f32_e32 v151, v151
	v_add_f32_e32 v209, v245, v209
	v_add_f32_e32 v209, v193, v209
	s_waitcnt lgkmcnt(2)
	v_mfma_f32_32x32x16_bf16 v[64:79], v[226:229], v[112:115], v[64:79]
	ds_read_b128 v[222:225], v203 offset:49152
	ds_read_b128 v[226:229], v203 offset:57344
	v_add_f32_e32 v209, v156, v209
	v_add_f32_e32 v209, v157, v209
	v_add_f32_e32 v209, v154, v209
	v_add_f32_e32 v209, v155, v209
	v_cvt_pk_bf16_f32 v160, v238, v239
	v_cvt_pk_bf16_f32 v162, v247, v248
	s_waitcnt lgkmcnt(3)
	v_mfma_f32_32x32x16_bf16 v[80:95], v[214:217], v[108:111], v[80:95]
	v_add_f32_e32 v209, v148, v209
	v_add_f32_e32 v209, v149, v209
	v_add_f32_e32 v209, v146, v209
	v_add_f32_e32 v209, v147, v209
	v_cvt_pk_bf16_f32 v161, v240, v246
	v_cvt_pk_bf16_f32 v163, v249, v250
	s_waitcnt lgkmcnt(2)
	v_mfma_f32_32x32x16_bf16 v[64:79], v[218:221], v[108:111], v[64:79]
	ds_read_b128 v[214:217], v206 offset:49152
	ds_read_b128 v[218:221], v206 offset:57344
	v_add_f32_e32 v209, v144, v209
	v_add_f32_e32 v209, v145, v209
	v_add_f32_e32 v209, v158, v209
	v_add_f32_e32 v209, v159, v209
	v_permlane32_swap_b32_e32 v160, v162
	v_permlane32_swap_b32_e32 v161, v163
	s_waitcnt lgkmcnt(3)
	v_mfma_f32_32x32x16_bf16 v[80:95], v[222:225], v[104:107], v[80:95]
	v_add_f32_e32 v209, v152, v209
	v_add_f32_e32 v209, v153, v209
	v_add_f32_e32 v209, v150, v209
	v_add_f32_e32 v209, v151, v209
	v_cvt_pk_bf16_f32 v170, v251, v252
	v_cvt_pk_bf16_f32 v172, v243, v244
	s_waitcnt lgkmcnt(2)
	v_mfma_f32_32x32x16_bf16 v[64:79], v[226:229], v[104:107], v[64:79]
	ds_read_b128 v[222:225], v207 offset:49152
	ds_read_b128 v[226:229], v207 offset:57344
	s_waitcnt vmcnt(0)
	v_add_u32_e32 v196, s92, v183
	v_add_u32_e32 v198, s92, v184
	ds_write_b128 v188, v[136:139] offset:32768
	ds_write_b128 v189, v[140:143] offset:32768
	ds_write_b128 v196, v[128:131]
	ds_write_b128 v198, v[132:135]
	v_mov_b32_e32 v210, v209
	v_cvt_pk_bf16_f32 v171, v253, v241
	v_cvt_pk_bf16_f32 v173, v245, v193
	v_cvt_pk_bf16_f32 v166, v156, v157
	v_cvt_pk_bf16_f32 v168, v148, v149
	s_waitcnt lgkmcnt(7)
	v_mfma_f32_32x32x16_bf16 v[80:95], v[214:217], v[100:103], v[80:95]
	v_permlane32_swap_b32_e32 v209, v210
	v_permlane32_swap_b32_e32 v170, v172
	v_permlane32_swap_b32_e32 v171, v173
	v_cvt_pk_bf16_f32 v167, v154, v155
	v_cvt_pk_bf16_f32 v169, v146, v147
	s_waitcnt lgkmcnt(6)
	v_mfma_f32_32x32x16_bf16 v[64:79], v[218:221], v[100:103], v[64:79]
	v_permlane32_swap_b32_e32 v166, v168
	v_cvt_pk_bf16_f32 v212, v144, v145
	v_cvt_pk_bf16_f32 v213, v158, v159
	s_waitcnt lgkmcnt(5)
	v_mfma_f32_32x32x16_bf16 v[80:95], v[222:225], v[96:99], v[80:95]
	v_permlane32_swap_b32_e32 v167, v169
	v_cvt_pk_bf16_f32 v214, v152, v153
	v_cvt_pk_bf16_f32 v215, v150, v151
	s_waitcnt lgkmcnt(4)
	v_mfma_f32_32x32x16_bf16 v[64:79], v[226:229], v[96:99], v[64:79]
	v_permlane32_swap_b32_e32 v212, v214
	v_permlane32_swap_b32_e32 v213, v215
	v_add_u32_e32 v187, s90, v182
	ds_read_b64_tr_b16 v[216:217], v187 offset:0
	ds_read_b64_tr_b16 v[218:219], v187 offset:0x800
	ds_read_b64_tr_b16 v[220:221], v187 offset:0x1000
	ds_read_b64_tr_b16 v[222:223], v187 offset:0x1800
	ds_read_b64_tr_b16 v[224:225], v187 offset:0x2000
	ds_read_b64_tr_b16 v[226:227], v187 offset:0x2800
	ds_read_b64_tr_b16 v[228:229], v187 offset:0x3000
	ds_read_b64_tr_b16 v[230:231], v187 offset:0x3800
	s_mov_b32 s2, 0xfffb8000
	v_add_co_u32_e32 v148, vcc, s2, v178
	s_mov_b32 s2, 0xfffd0000
	s_nop 0
	v_addc_co_u32_e32 v149, vcc, -1, v179, vcc
	v_add_co_u32_e32 v152, vcc, s2, v178
	s_nop 1
	v_addc_co_u32_e32 v153, vcc, -1, v179, vcc
	global_load_dwordx4 v[144:147], v[148:149], off
	s_nop 0
	global_load_dwordx4 v[148:151], v[148:149], off offset:-512
	s_nop 0
	global_load_dwordx4 v[156:159], v[152:153], off
	s_nop 0
	global_load_dwordx4 v[152:155], v[152:153], off offset:-512
	v_max_f32_e32 v196, v81, v81
	v_max_f32_e32 v197, v80, v80
	v_max_f32_e32 v196, v197, v196
	v_max3_f32 v196, v196, v82, v83
	v_max3_f32 v196, v196, v84, v85
	v_max3_f32 v196, v196, v86, v87
	v_max3_f32 v196, v196, v88, v89
	s_waitcnt lgkmcnt(0)
	s_barrier
	v_mfma_f32_32x32x16_bf16 v[0:15], v[160:163], v[216:219], v[0:15]
	ds_read_b64_tr_b16 v[216:217], v187 offset:0x200
	ds_read_b64_tr_b16 v[218:219], v187 offset:0xa00
	v_max3_f32 v196, v196, v90, v91
	v_max3_f32 v196, v196, v92, v93
	v_max3_f32 v196, v196, v94, v95
	v_max3_f32 v196, v196, v64, v65
	v_mfma_f32_32x32x16_bf16 v[0:15], v[170:173], v[220:223], v[0:15]
	ds_read_b64_tr_b16 v[220:221], v187 offset:0x1200
	ds_read_b64_tr_b16 v[222:223], v187 offset:0x1a00
	v_max3_f32 v196, v196, v66, v67
	v_max3_f32 v196, v196, v68, v69
	v_max3_f32 v196, v196, v70, v71
	v_max3_f32 v196, v196, v72, v73
	v_mfma_f32_32x32x16_bf16 v[0:15], v[166:169], v[224:227], v[0:15]
	ds_read_b64_tr_b16 v[224:225], v187 offset:0x2200
	ds_read_b64_tr_b16 v[226:227], v187 offset:0x2a00
	v_max3_f32 v196, v196, v74, v75
	v_max3_f32 v196, v196, v76, v77
	v_max3_f32 v196, v196, v78, v79
	v_mov_b32_e32 v197, v196
	v_mfma_f32_32x32x16_bf16 v[0:15], v[212:215], v[228:231], v[0:15]
	ds_read_b64_tr_b16 v[228:229], v187 offset:0x3200
	ds_read_b64_tr_b16 v[230:231], v187 offset:0x3a00
	v_permlane32_swap_b32_e32 v196, v197
	v_max_f32_e32 v197, v197, v197
	v_max_f32_e32 v196, v196, v196
	v_max_f32_e32 v196, v196, v197
	s_waitcnt lgkmcnt(0)
	v_mfma_f32_32x32x16_bf16 v[48:63], v[160:163], v[216:219], v[48:63]
	ds_read_b64_tr_b16 v[216:217], v187 offset:0x400
	ds_read_b64_tr_b16 v[218:219], v187 offset:0xc00
	v_sub_f32_e32 v197, v196, v164
	v_cmp_ge_f32_e32 vcc, s85, v197
	v_max_f32_e32 v197, v164, v164
	v_max_f32_e32 v196, v197, v196
	v_sub_f32_e32 v197, v164, v196
	v_mul_f32_e32 v197, 0x3e0293ee, v197
	v_mfma_f32_32x32x16_bf16 v[48:63], v[170:173], v[220:223], v[48:63]
	ds_read_b64_tr_b16 v[220:221], v187 offset:0x1400
	ds_read_b64_tr_b16 v[222:223], v187 offset:0x1c00
	v_exp_f32_e32 v197, v197
	s_cmp_eq_u64 vcc, exec
	s_cselect_b64 s[42:43], -1, 0
	v_mfma_f32_32x32x16_bf16 v[48:63], v[166:169], v[224:227], v[48:63]
	ds_read_b64_tr_b16 v[224:225], v187 offset:0x2400
	ds_read_b64_tr_b16 v[226:227], v187 offset:0x2c00
	v_cndmask_b32_e64 v211, v196, v164, s[42:43]
	v_mul_f32_e32 v198, 0xbe0293ee, v211
	v_fmamk_f32 v80, v80, 0x3e0293ee, v198
	v_fmamk_f32 v81, v81, 0x3e0293ee, v198
	v_fmamk_f32 v82, v82, 0x3e0293ee, v198
	v_fmamk_f32 v83, v83, 0x3e0293ee, v198
	v_mfma_f32_32x32x16_bf16 v[48:63], v[212:215], v[228:231], v[48:63]
	ds_read_b64_tr_b16 v[228:229], v187 offset:0x3400
	ds_read_b64_tr_b16 v[230:231], v187 offset:0x3c00
	v_fmamk_f32 v84, v84, 0x3e0293ee, v198
	v_fmamk_f32 v85, v85, 0x3e0293ee, v198
	v_fmamk_f32 v86, v86, 0x3e0293ee, v198
	v_fmamk_f32 v87, v87, 0x3e0293ee, v198
	v_exp_f32_e32 v238, v80
	v_exp_f32_e32 v239, v81
	s_waitcnt lgkmcnt(0)
	v_mfma_f32_32x32x16_bf16 v[32:47], v[160:163], v[216:219], v[32:47]
	ds_read_b64_tr_b16 v[216:217], v187 offset:0x600
	ds_read_b64_tr_b16 v[218:219], v187 offset:0xe00
	v_fmamk_f32 v88, v88, 0x3e0293ee, v198
	v_fmamk_f32 v89, v89, 0x3e0293ee, v198
	v_fmamk_f32 v90, v90, 0x3e0293ee, v198
	v_fmamk_f32 v91, v91, 0x3e0293ee, v198
	v_exp_f32_e32 v240, v82
	v_exp_f32_e32 v246, v83
	v_mfma_f32_32x32x16_bf16 v[32:47], v[170:173], v[220:223], v[32:47]
	ds_read_b64_tr_b16 v[220:221], v187 offset:0x1600
	ds_read_b64_tr_b16 v[222:223], v187 offset:0x1e00
	v_fmamk_f32 v92, v92, 0x3e0293ee, v198
	v_fmamk_f32 v93, v93, 0x3e0293ee, v198
	v_fmamk_f32 v94, v94, 0x3e0293ee, v198
	v_fmamk_f32 v95, v95, 0x3e0293ee, v198
	v_exp_f32_e32 v247, v84
	v_exp_f32_e32 v248, v85
	v_mfma_f32_32x32x16_bf16 v[32:47], v[166:169], v[224:227], v[32:47]
	ds_read_b64_tr_b16 v[224:225], v187 offset:0x2600
	ds_read_b64_tr_b16 v[226:227], v187 offset:0x2e00
	v_exp_f32_e32 v249, v86
	v_exp_f32_e32 v250, v87
	v_exp_f32_e32 v251, v88
	v_mfma_f32_32x32x16_bf16 v[32:47], v[212:215], v[228:231], v[32:47]
	ds_read_b64_tr_b16 v[228:229], v187 offset:0x3600
	ds_read_b64_tr_b16 v[230:231], v187 offset:0x3e00
	v_exp_f32_e32 v252, v89
	v_exp_f32_e32 v253, v90
	v_exp_f32_e32 v241, v91
	s_waitcnt lgkmcnt(0)
	v_mfma_f32_32x32x16_bf16 v[16:31], v[160:163], v[216:219], v[16:31]
	v_exp_f32_e32 v243, v92
	v_exp_f32_e32 v244, v93
	v_mfma_f32_32x32x16_bf16 v[16:31], v[170:173], v[220:223], v[16:31]
	v_exp_f32_e32 v245, v94
	v_exp_f32_e32 v193, v95
	v_mfma_f32_32x32x16_bf16 v[16:31], v[166:169], v[224:227], v[16:31]
	v_mfma_f32_32x32x16_bf16 v[16:31], v[212:215], v[228:231], v[16:31]
	v_cndmask_b32_e64 v213, v197, 1.0, s[42:43]
	v_cmp_gt_f32_e32 vcc, 1.0, v213
	v_mul_f32_e32 v212, 0xbe0293ee, v211
	s_add_i32 s11, s11, 2
	s_nop 3
	s_cbranch_vccz .LBB0_730
	s_and_saveexec_b64 s[2:3], s[40:41]
	ds_write_b32 v185, v213 offset:128
	s_or_b64 exec, exec, s[2:3]
	s_waitcnt lgkmcnt(0)
	v_add_u32_e32 v161, v177, v194
	ds_read_b128 v[166:169], v161 offset:224
	ds_read_b128 v[170:173], v161 offset:192
	ds_read_b128 v[214:217], v161 offset:160
	ds_read_b128 v[218:221], v161 offset:128
	s_waitcnt lgkmcnt(3)
	v_pk_mul_f32 v[12:13], v[12:13], v[166:167]
	s_waitcnt lgkmcnt(2)
	v_pk_mul_f32 v[8:9], v[8:9], v[170:171]
	s_waitcnt lgkmcnt(1)
	v_pk_mul_f32 v[4:5], v[4:5], v[214:215]
	v_pk_mul_f32 v[14:15], v[14:15], v[168:169]
	v_pk_mul_f32 v[10:11], v[10:11], v[172:173]
	v_pk_mul_f32 v[6:7], v[6:7], v[216:217]
	s_waitcnt lgkmcnt(0)
	v_pk_mul_f32 v[2:3], v[2:3], v[220:221]
	v_pk_mul_f32 v[0:1], v[0:1], v[218:219]
	v_pk_mul_f32 v[60:61], v[60:61], v[166:167]
	v_pk_mul_f32 v[56:57], v[56:57], v[170:171]
	v_pk_mul_f32 v[52:53], v[52:53], v[214:215]
	v_pk_mul_f32 v[62:63], v[62:63], v[168:169]
	v_pk_mul_f32 v[58:59], v[58:59], v[172:173]
	v_pk_mul_f32 v[54:55], v[54:55], v[216:217]
	v_pk_mul_f32 v[50:51], v[50:51], v[220:221]
	v_pk_mul_f32 v[48:49], v[48:49], v[218:219]
	v_pk_mul_f32 v[44:45], v[44:45], v[166:167]
	v_pk_mul_f32 v[40:41], v[40:41], v[170:171]
	v_pk_mul_f32 v[36:37], v[36:37], v[214:215]
	v_pk_mul_f32 v[46:47], v[46:47], v[168:169]
	v_pk_mul_f32 v[42:43], v[42:43], v[172:173]
	v_pk_mul_f32 v[38:39], v[38:39], v[216:217]
	v_pk_mul_f32 v[34:35], v[34:35], v[220:221]
	v_pk_mul_f32 v[32:33], v[32:33], v[218:219]
	v_pk_mul_f32 v[28:29], v[28:29], v[166:167]
	v_pk_mul_f32 v[24:25], v[24:25], v[170:171]
	v_pk_mul_f32 v[20:21], v[20:21], v[214:215]
	v_pk_mul_f32 v[30:31], v[30:31], v[168:169]
	v_pk_mul_f32 v[26:27], v[26:27], v[172:173]
	v_pk_mul_f32 v[22:23], v[22:23], v[216:217]
	v_pk_mul_f32 v[18:19], v[18:19], v[220:221]
	v_pk_mul_f32 v[16:17], v[16:17], v[218:219]
.LBB0_730:
	ds_read_b128 v[128:131], v190 offset:32768
	ds_read_b128 v[132:135], v190 offset:40960
	ds_read_b128 v[136:139], v205 offset:32768
	ds_read_b128 v[140:143], v205 offset:40960
	v_fmamk_f32 v215, v69, 0x3e0293ee, v212
	v_fmamk_f32 v214, v76, 0x3e0293ee, v212
	v_fmamk_f32 v222, v64, 0x3e0293ee, v212
	v_fmamk_f32 v223, v65, 0x3e0293ee, v212
	v_fmamk_f32 v224, v66, 0x3e0293ee, v212
	v_fmamk_f32 v225, v67, 0x3e0293ee, v212
	v_fmamk_f32 v226, v68, 0x3e0293ee, v212
	v_fmamk_f32 v216, v70, 0x3e0293ee, v212
	v_fmamk_f32 v217, v71, 0x3e0293ee, v212
	v_fmamk_f32 v218, v72, 0x3e0293ee, v212
	v_fmamk_f32 v219, v73, 0x3e0293ee, v212
	v_fmamk_f32 v220, v74, 0x3e0293ee, v212
	v_fmamk_f32 v221, v75, 0x3e0293ee, v212
	v_fmamk_f32 v227, v77, 0x3e0293ee, v212
	v_fmamk_f32 v228, v78, 0x3e0293ee, v212
	v_fmac_f32_e32 v212, 0x3e0293ee, v79
	v_exp_f32_e32 v222, v222
	v_exp_f32_e32 v223, v223
	v_add_f32_e32 v196, v238, v239
	s_waitcnt lgkmcnt(3)
	v_mfma_f32_32x32x16_bf16 v[80:95], v[128:131], v[124:127], 0
	v_exp_f32_e32 v224, v224
	v_exp_f32_e32 v225, v225
	v_add_f32_e32 v196, v240, v196
	v_add_f32_e32 v196, v246, v196
	s_waitcnt lgkmcnt(2)
	v_mfma_f32_32x32x16_bf16 v[64:79], v[132:135], v[124:127], 0
	ds_read_b128 v[128:131], v204 offset:32768
	ds_read_b128 v[132:135], v204 offset:40960
	v_exp_f32_e32 v226, v226
	v_exp_f32_e32 v215, v215
	v_add_f32_e32 v196, v247, v196
	v_add_f32_e32 v196, v248, v196
	s_waitcnt lgkmcnt(3)
	v_mfma_f32_32x32x16_bf16 v[80:95], v[136:139], v[120:123], v[80:95]
	v_exp_f32_e32 v216, v216
	v_exp_f32_e32 v217, v217
	v_add_f32_e32 v196, v249, v196
	v_add_f32_e32 v196, v250, v196
	s_waitcnt lgkmcnt(2)
	v_mfma_f32_32x32x16_bf16 v[64:79], v[140:143], v[120:123], v[64:79]
	ds_read_b128 v[136:139], v202 offset:32768
	ds_read_b128 v[140:143], v202 offset:40960
	v_exp_f32_e32 v218, v218
	v_exp_f32_e32 v219, v219
	v_add_f32_e32 v196, v251, v196
	v_add_f32_e32 v196, v252, v196
	s_waitcnt lgkmcnt(3)
	v_mfma_f32_32x32x16_bf16 v[80:95], v[128:131], v[116:119], v[80:95]
	v_exp_f32_e32 v220, v220
	v_exp_f32_e32 v221, v221
	v_add_f32_e32 v196, v253, v196
	v_add_f32_e32 v196, v241, v196
	s_waitcnt lgkmcnt(2)
	v_mfma_f32_32x32x16_bf16 v[64:79], v[132:135], v[116:119], v[64:79]
	ds_read_b128 v[128:131], v191 offset:32768
	ds_read_b128 v[132:135], v191 offset:40960
	v_exp_f32_e32 v214, v214
	v_exp_f32_e32 v227, v227
	v_add_f32_e32 v196, v243, v196
	v_add_f32_e32 v196, v244, v196
	s_waitcnt lgkmcnt(3)
	v_mfma_f32_32x32x16_bf16 v[80:95], v[136:139], v[112:115], v[80:95]
	v_exp_f32_e32 v228, v228
	v_exp_f32_e32 v212, v212
	v_add_f32_e32 v196, v245, v196
	v_add_f32_e32 v196, v193, v196
	s_waitcnt lgkmcnt(2)
	v_mfma_f32_32x32x16_bf16 v[64:79], v[140:143], v[112:115], v[64:79]
	ds_read_b128 v[136:139], v203 offset:32768
	ds_read_b128 v[140:143], v203 offset:40960
	v_add_f32_e32 v196, v222, v196
	v_add_f32_e32 v196, v223, v196
	v_add_f32_e32 v196, v224, v196
	v_add_f32_e32 v196, v225, v196
	v_cvt_pk_bf16_f32 v160, v238, v239
	v_cvt_pk_bf16_f32 v162, v247, v248
	s_waitcnt lgkmcnt(3)
	v_mfma_f32_32x32x16_bf16 v[80:95], v[128:131], v[108:111], v[80:95]
	v_add_f32_e32 v196, v226, v196
	v_add_f32_e32 v196, v215, v196
	v_add_f32_e32 v196, v216, v196
	v_add_f32_e32 v196, v217, v196
	v_cvt_pk_bf16_f32 v161, v240, v246
	v_cvt_pk_bf16_f32 v163, v249, v250
	s_waitcnt lgkmcnt(2)
	v_mfma_f32_32x32x16_bf16 v[64:79], v[132:135], v[108:111], v[64:79]
	ds_read_b128 v[128:131], v206 offset:32768
	ds_read_b128 v[132:135], v206 offset:40960
	v_add_f32_e32 v196, v218, v196
	v_add_f32_e32 v196, v219, v196
	v_add_f32_e32 v196, v220, v196
	v_add_f32_e32 v196, v221, v196
	v_permlane32_swap_b32_e32 v160, v162
	v_permlane32_swap_b32_e32 v161, v163
	s_waitcnt lgkmcnt(3)
	v_mfma_f32_32x32x16_bf16 v[80:95], v[136:139], v[104:107], v[80:95]
	v_add_f32_e32 v196, v214, v196
	v_add_f32_e32 v196, v227, v196
	v_add_f32_e32 v196, v228, v196
	v_add_f32_e32 v196, v212, v196
	v_cvt_pk_bf16_f32 v164, v251, v252
	v_cvt_pk_bf16_f32 v166, v243, v244
	s_waitcnt lgkmcnt(2)
	v_mfma_f32_32x32x16_bf16 v[64:79], v[140:143], v[104:107], v[64:79]
	ds_read_b128 v[136:139], v207 offset:32768
	ds_read_b128 v[140:143], v207 offset:40960
	s_waitcnt vmcnt(0)
	ds_write_b128 v188, v[148:151] offset:49152
	ds_write_b128 v189, v[152:155] offset:49152
	v_add_u32_e32 v197, s99, v183
	ds_write_b128 v197, v[144:147]
	v_add_u32_e32 v197, s99, v184
	ds_write_b128 v197, v[156:159]
	v_mov_b32_e32 v198, v196
	v_cvt_pk_bf16_f32 v165, v253, v241
	v_cvt_pk_bf16_f32 v167, v245, v193
	v_cvt_pk_bf16_f32 v168, v222, v223
	v_cvt_pk_bf16_f32 v170, v226, v215
	s_waitcnt lgkmcnt(7)
	v_mfma_f32_32x32x16_bf16 v[80:95], v[128:131], v[100:103], v[80:95]
	v_permlane32_swap_b32_e32 v196, v198
	v_permlane32_swap_b32_e32 v164, v166
	v_permlane32_swap_b32_e32 v165, v167
	v_cvt_pk_bf16_f32 v169, v224, v225
	v_cvt_pk_bf16_f32 v171, v216, v217
	s_waitcnt lgkmcnt(6)
	v_mfma_f32_32x32x16_bf16 v[64:79], v[132:135], v[100:103], v[64:79]
	v_permlane32_swap_b32_e32 v168, v170
	v_cvt_pk_bf16_f32 v172, v218, v219
	v_cvt_pk_bf16_f32 v173, v220, v221
	s_waitcnt lgkmcnt(5)
	v_mfma_f32_32x32x16_bf16 v[80:95], v[136:139], v[96:99], v[80:95]
	v_permlane32_swap_b32_e32 v169, v171
	v_cvt_pk_bf16_f32 v174, v214, v227
	v_cvt_pk_bf16_f32 v175, v228, v212
	s_waitcnt lgkmcnt(4)
	v_mfma_f32_32x32x16_bf16 v[64:79], v[140:143], v[96:99], v[64:79]
	v_permlane32_swap_b32_e32 v172, v174
	v_permlane32_swap_b32_e32 v173, v175
	v_add_f32_e32 v209, v209, v210
	v_fmac_f32_e32 v209, v208, v186
	v_add_f32_e32 v186, v196, v198
	v_fmac_f32_e32 v186, v209, v213
	v_add_u32_e32 v187, s91, v182
	ds_read_b64_tr_b16 v[216:217], v187 offset:0
	ds_read_b64_tr_b16 v[218:219], v187 offset:0x800
	ds_read_b64_tr_b16 v[220:221], v187 offset:0x1000
	ds_read_b64_tr_b16 v[222:223], v187 offset:0x1800
	ds_read_b64_tr_b16 v[224:225], v187 offset:0x2000
	ds_read_b64_tr_b16 v[226:227], v187 offset:0x2800
	ds_read_b64_tr_b16 v[228:229], v187 offset:0x3000
	ds_read_b64_tr_b16 v[230:231], v187 offset:0x3800
	s_cmpk_gt_u32 s11, 0x7c
	s_cselect_b64 s[20:21], -1, 0
	s_and_b64 vcc, exec, s[20:21]
	s_cbranch_vccnz .LBB0_732
	v_add_co_u32_e32 v132, vcc, 0xfffe8000, v178
	s_nop 1
	v_addc_co_u32_e32 v133, vcc, -1, v179, vcc
	global_load_dwordx4 v[128:131], v[132:133], off
	global_load_dwordx4 v[136:139], v[132:133], off offset:-512
	s_nop 0
	global_load_dwordx4 v[132:135], v[178:179], off
	global_load_dwordx4 v[140:143], v[178:179], off offset:-512
.LBB0_732:
	v_max_f32_e32 v196, v81, v81
	v_max_f32_e32 v197, v80, v80
	v_max_f32_e32 v196, v197, v196
	v_max3_f32 v196, v196, v82, v83
	v_max3_f32 v196, v196, v84, v85
	v_max3_f32 v196, v196, v86, v87
	v_max3_f32 v196, v196, v88, v89
	s_waitcnt lgkmcnt(0)
	s_barrier
	v_mfma_f32_32x32x16_bf16 v[0:15], v[160:163], v[216:219], v[0:15]
	ds_read_b64_tr_b16 v[216:217], v187 offset:0x200
	ds_read_b64_tr_b16 v[218:219], v187 offset:0xa00
	v_max3_f32 v196, v196, v90, v91
	v_max3_f32 v196, v196, v92, v93
	v_max3_f32 v196, v196, v94, v95
	v_max3_f32 v196, v196, v64, v65
	v_mfma_f32_32x32x16_bf16 v[0:15], v[164:167], v[220:223], v[0:15]
	ds_read_b64_tr_b16 v[220:221], v187 offset:0x1200
	ds_read_b64_tr_b16 v[222:223], v187 offset:0x1a00
	v_max3_f32 v196, v196, v66, v67
	v_max3_f32 v196, v196, v68, v69
	v_max3_f32 v196, v196, v70, v71
	v_max3_f32 v196, v196, v72, v73
	v_mfma_f32_32x32x16_bf16 v[0:15], v[168:171], v[224:227], v[0:15]
	ds_read_b64_tr_b16 v[224:225], v187 offset:0x2200
	ds_read_b64_tr_b16 v[226:227], v187 offset:0x2a00
	v_max3_f32 v196, v196, v74, v75
	v_max3_f32 v196, v196, v76, v77
	v_max3_f32 v196, v196, v78, v79
	v_mov_b32_e32 v197, v196
	v_mfma_f32_32x32x16_bf16 v[0:15], v[172:175], v[228:231], v[0:15]
	ds_read_b64_tr_b16 v[228:229], v187 offset:0x3200
	ds_read_b64_tr_b16 v[230:231], v187 offset:0x3a00
	v_permlane32_swap_b32_e32 v196, v197
	v_max_f32_e32 v197, v197, v197
	v_max_f32_e32 v196, v196, v196
	v_max_f32_e32 v196, v196, v197
	s_waitcnt lgkmcnt(0)
	v_mfma_f32_32x32x16_bf16 v[48:63], v[160:163], v[216:219], v[48:63]
	ds_read_b64_tr_b16 v[216:217], v187 offset:0x400
	ds_read_b64_tr_b16 v[218:219], v187 offset:0xc00
	v_sub_f32_e32 v197, v196, v211
	v_cmp_ge_f32_e32 vcc, s85, v197
	v_max_f32_e32 v197, v211, v211
	v_max_f32_e32 v197, v197, v196
	v_sub_f32_e32 v196, v211, v197
	v_mul_f32_e32 v196, 0x3e0293ee, v196
	v_mfma_f32_32x32x16_bf16 v[48:63], v[164:167], v[220:223], v[48:63]
	ds_read_b64_tr_b16 v[220:221], v187 offset:0x1400
	ds_read_b64_tr_b16 v[222:223], v187 offset:0x1c00
	v_exp_f32_e32 v196, v196
	s_cmp_eq_u64 vcc, exec
	s_cselect_b64 s[42:43], -1, 0
	v_mfma_f32_32x32x16_bf16 v[48:63], v[168:171], v[224:227], v[48:63]
	ds_read_b64_tr_b16 v[224:225], v187 offset:0x2400
	ds_read_b64_tr_b16 v[226:227], v187 offset:0x2c00
	v_cndmask_b32_e64 v197, v197, v211, s[42:43]
	v_mul_f32_e32 v198, 0xbe0293ee, v197
	v_fmamk_f32 v80, v80, 0x3e0293ee, v198
	v_fmamk_f32 v81, v81, 0x3e0293ee, v198
	v_fmamk_f32 v82, v82, 0x3e0293ee, v198
	v_fmamk_f32 v83, v83, 0x3e0293ee, v198
	v_mfma_f32_32x32x16_bf16 v[48:63], v[172:175], v[228:231], v[48:63]
	ds_read_b64_tr_b16 v[228:229], v187 offset:0x3400
	ds_read_b64_tr_b16 v[230:231], v187 offset:0x3c00
	v_fmamk_f32 v84, v84, 0x3e0293ee, v198
	v_fmamk_f32 v85, v85, 0x3e0293ee, v198
	v_fmamk_f32 v86, v86, 0x3e0293ee, v198
	v_fmamk_f32 v87, v87, 0x3e0293ee, v198
	v_exp_f32_e32 v238, v80
	v_exp_f32_e32 v239, v81
	s_waitcnt lgkmcnt(0)
	v_mfma_f32_32x32x16_bf16 v[32:47], v[160:163], v[216:219], v[32:47]
	ds_read_b64_tr_b16 v[216:217], v187 offset:0x600
	ds_read_b64_tr_b16 v[218:219], v187 offset:0xe00
	v_fmamk_f32 v88, v88, 0x3e0293ee, v198
	v_fmamk_f32 v89, v89, 0x3e0293ee, v198
	v_fmamk_f32 v90, v90, 0x3e0293ee, v198
	v_fmamk_f32 v91, v91, 0x3e0293ee, v198
	v_exp_f32_e32 v240, v82
	v_exp_f32_e32 v246, v83
	v_mfma_f32_32x32x16_bf16 v[32:47], v[164:167], v[220:223], v[32:47]
	ds_read_b64_tr_b16 v[220:221], v187 offset:0x1600
	ds_read_b64_tr_b16 v[222:223], v187 offset:0x1e00
	v_fmamk_f32 v92, v92, 0x3e0293ee, v198
	v_fmamk_f32 v93, v93, 0x3e0293ee, v198
	v_fmamk_f32 v94, v94, 0x3e0293ee, v198
	v_fmamk_f32 v95, v95, 0x3e0293ee, v198
	v_exp_f32_e32 v247, v84
	v_exp_f32_e32 v248, v85
	v_mfma_f32_32x32x16_bf16 v[32:47], v[168:171], v[224:227], v[32:47]
	ds_read_b64_tr_b16 v[224:225], v187 offset:0x2600
	ds_read_b64_tr_b16 v[226:227], v187 offset:0x2e00
	v_exp_f32_e32 v249, v86
	v_exp_f32_e32 v250, v87
	v_exp_f32_e32 v251, v88
	v_mfma_f32_32x32x16_bf16 v[32:47], v[172:175], v[228:231], v[32:47]
	ds_read_b64_tr_b16 v[228:229], v187 offset:0x3600
	ds_read_b64_tr_b16 v[230:231], v187 offset:0x3e00
	v_exp_f32_e32 v252, v89
	v_exp_f32_e32 v253, v90
	v_exp_f32_e32 v241, v91
	s_waitcnt lgkmcnt(0)
	v_mfma_f32_32x32x16_bf16 v[16:31], v[160:163], v[216:219], v[16:31]
	v_exp_f32_e32 v243, v92
	v_exp_f32_e32 v244, v93
	v_mfma_f32_32x32x16_bf16 v[16:31], v[164:167], v[220:223], v[16:31]
	v_exp_f32_e32 v245, v94
	v_exp_f32_e32 v193, v95
	v_mfma_f32_32x32x16_bf16 v[16:31], v[168:171], v[224:227], v[16:31]
	v_mfma_f32_32x32x16_bf16 v[16:31], v[172:175], v[228:231], v[16:31]
	v_cndmask_b32_e64 v160, v196, 1.0, s[42:43]
	v_cmp_gt_f32_e32 vcc, 1.0, v160
	v_mov_b32_e32 v164, v197
	s_mov_b32 s98, s90
	s_mov_b32 s90, s92
	s_mov_b32 s92, s98
	s_mov_b32 s98, s91
	s_mov_b32 s91, s99
	s_mov_b32 s99, s98
	s_cbranch_vccz .LBB0_736
	s_and_saveexec_b64 s[2:3], s[40:41]
	ds_write_b32 v185, v160 offset:128
	s_or_b64 exec, exec, s[2:3]
	s_waitcnt lgkmcnt(0)
	v_add_u32_e32 v156, v177, v194
	ds_read_b128 v[144:147], v156 offset:224
	ds_read_b128 v[148:151], v156 offset:192
	ds_read_b128 v[152:155], v156 offset:160
	ds_read_b128 v[156:159], v156 offset:128
	s_waitcnt lgkmcnt(3)
	v_pk_mul_f32 v[12:13], v[12:13], v[144:145]
	s_waitcnt lgkmcnt(2)
	v_pk_mul_f32 v[8:9], v[8:9], v[148:149]
	s_waitcnt lgkmcnt(1)
	v_pk_mul_f32 v[4:5], v[4:5], v[152:153]
	v_pk_mul_f32 v[14:15], v[14:15], v[146:147]
	v_pk_mul_f32 v[10:11], v[10:11], v[150:151]
	v_pk_mul_f32 v[6:7], v[6:7], v[154:155]
	s_waitcnt lgkmcnt(0)
	v_pk_mul_f32 v[2:3], v[2:3], v[158:159]
	v_pk_mul_f32 v[0:1], v[0:1], v[156:157]
	v_pk_mul_f32 v[60:61], v[60:61], v[144:145]
	v_pk_mul_f32 v[56:57], v[56:57], v[148:149]
	v_pk_mul_f32 v[52:53], v[52:53], v[152:153]
	v_pk_mul_f32 v[62:63], v[62:63], v[146:147]
	v_pk_mul_f32 v[58:59], v[58:59], v[150:151]
	v_pk_mul_f32 v[54:55], v[54:55], v[154:155]
	v_pk_mul_f32 v[50:51], v[50:51], v[158:159]
	v_pk_mul_f32 v[48:49], v[48:49], v[156:157]
	v_pk_mul_f32 v[44:45], v[44:45], v[144:145]
	v_pk_mul_f32 v[40:41], v[40:41], v[148:149]
	v_pk_mul_f32 v[36:37], v[36:37], v[152:153]
	v_pk_mul_f32 v[46:47], v[46:47], v[146:147]
	v_pk_mul_f32 v[42:43], v[42:43], v[150:151]
	v_pk_mul_f32 v[38:39], v[38:39], v[154:155]
	v_pk_mul_f32 v[34:35], v[34:35], v[158:159]
	v_pk_mul_f32 v[32:33], v[32:33], v[156:157]
	v_pk_mul_f32 v[28:29], v[28:29], v[144:145]
	v_pk_mul_f32 v[24:25], v[24:25], v[148:149]
	v_pk_mul_f32 v[20:21], v[20:21], v[152:153]
	v_pk_mul_f32 v[30:31], v[30:31], v[146:147]
	v_pk_mul_f32 v[26:27], v[26:27], v[150:151]
	v_pk_mul_f32 v[22:23], v[22:23], v[154:155]
	v_pk_mul_f32 v[18:19], v[18:19], v[158:159]
	v_pk_mul_f32 v[16:17], v[16:17], v[156:157]
.LBB0_736:
	ds_read_b128 v[214:217], v190 offset:49152
	ds_read_b128 v[218:221], v190 offset:57344
	ds_read_b128 v[222:225], v205 offset:49152
	ds_read_b128 v[226:229], v205 offset:57344
	v_mul_f32_e32 v150, 0xbe0293ee, v164
	v_mov_b32_e32 v151, v150
	v_pk_fma_f32 v[156:157], v[64:65], s[12:13], v[150:151] op_sel_hi:[1,0,0]
	v_pk_fma_f32 v[154:155], v[66:67], s[12:13], v[150:151] op_sel_hi:[1,0,0]
	v_pk_fma_f32 v[148:149], v[68:69], s[12:13], v[150:151] op_sel_hi:[1,0,0]
	v_pk_fma_f32 v[146:147], v[70:71], s[12:13], v[150:151] op_sel_hi:[1,0,0]
	v_pk_fma_f32 v[144:145], v[72:73], s[12:13], v[150:151] op_sel_hi:[1,0,0]
	v_pk_fma_f32 v[158:159], v[74:75], s[12:13], v[150:151] op_sel_hi:[1,0,0]
	v_pk_fma_f32 v[152:153], v[76:77], s[12:13], v[150:151] op_sel_hi:[1,0,0]
	v_pk_fma_f32 v[150:151], v[78:79], s[12:13], v[150:151] op_sel_hi:[1,0,0]
	s_mov_b64 s[2:3], 0x60000
	v_lshl_add_u64 v[178:179], v[178:179], 0, s[2:3]
	s_and_b64 vcc, exec, s[20:21]
	s_cbranch_vccnz .LBB0_738
	v_mov_b32_e32 v208, v160
	s_branch .LBB0_726
.LBB0_738:
	v_add_u32_e32 v187, 0x14800, v182
	v_add_u32_e32 v182, 0x10800, v182
	ds_read_b128 v[64:67], v190 offset:49152
	ds_read_b128 v[68:71], v190 offset:57344
	s_waitcnt lgkmcnt(1)
	v_mfma_f32_32x32x16_bf16 v[80:95], v[64:67], v[124:127], 0
	s_waitcnt lgkmcnt(0)
	v_mfma_f32_32x32x16_bf16 v[64:79], v[68:71], v[124:127], 0
	ds_read_b128 v[124:127], v205 offset:49152
	ds_read_b128 v[128:131], v205 offset:57344
	s_waitcnt lgkmcnt(1)
	v_mfma_f32_32x32x16_bf16 v[80:95], v[124:127], v[120:123], v[80:95]
	s_waitcnt lgkmcnt(0)
	v_mfma_f32_32x32x16_bf16 v[64:79], v[128:131], v[120:123], v[64:79]
	ds_read_b128 v[120:123], v204 offset:49152
	ds_read_b128 v[124:127], v204 offset:57344
	s_waitcnt lgkmcnt(1)
	v_mfma_f32_32x32x16_bf16 v[80:95], v[120:123], v[116:119], v[80:95]
	s_waitcnt lgkmcnt(0)
	v_mfma_f32_32x32x16_bf16 v[64:79], v[124:127], v[116:119], v[64:79]
	ds_read_b128 v[116:119], v202 offset:49152
	ds_read_b128 v[120:123], v202 offset:57344
	s_waitcnt lgkmcnt(1)
	v_mfma_f32_32x32x16_bf16 v[80:95], v[116:119], v[112:115], v[80:95]
	s_waitcnt lgkmcnt(0)
	v_mfma_f32_32x32x16_bf16 v[64:79], v[120:123], v[112:115], v[64:79]
	ds_read_b128 v[112:115], v191 offset:49152
	ds_read_b128 v[116:119], v191 offset:57344
	v_exp_f32_e32 v120, v150
	v_exp_f32_e32 v121, v151
	s_waitcnt lgkmcnt(1)
	v_mfma_f32_32x32x16_bf16 v[80:95], v[112:115], v[108:111], v[80:95]
	s_waitcnt lgkmcnt(0)
	v_mfma_f32_32x32x16_bf16 v[64:79], v[116:119], v[108:111], v[64:79]
	ds_read_b128 v[108:111], v203 offset:49152
	ds_read_b128 v[112:115], v203 offset:57344
	v_exp_f32_e32 v116, v158
	v_exp_f32_e32 v117, v159
	v_exp_f32_e32 v118, v152
	v_exp_f32_e32 v119, v153
	s_waitcnt lgkmcnt(1)
	v_mfma_f32_32x32x16_bf16 v[80:95], v[108:111], v[104:107], v[80:95]
	s_waitcnt lgkmcnt(0)
	v_mfma_f32_32x32x16_bf16 v[64:79], v[112:115], v[104:107], v[64:79]
	ds_read_b128 v[104:107], v206 offset:49152
	ds_read_b128 v[108:111], v206 offset:57344
	v_exp_f32_e32 v112, v146
	v_exp_f32_e32 v113, v147
	v_exp_f32_e32 v114, v144
	v_exp_f32_e32 v115, v145
	s_waitcnt lgkmcnt(1)
	v_mfma_f32_32x32x16_bf16 v[80:95], v[104:107], v[100:103], v[80:95]
	s_waitcnt lgkmcnt(0)
	v_mfma_f32_32x32x16_bf16 v[64:79], v[108:111], v[100:103], v[64:79]
	ds_read_b128 v[100:103], v207 offset:49152
	ds_read_b128 v[104:107], v207 offset:57344
	v_exp_f32_e32 v108, v154
	v_exp_f32_e32 v109, v155
	v_exp_f32_e32 v110, v148
	v_exp_f32_e32 v111, v149
	s_waitcnt lgkmcnt(1)
	v_mfma_f32_32x32x16_bf16 v[80:95], v[100:103], v[96:99], v[80:95]
	s_waitcnt lgkmcnt(0)
	v_mfma_f32_32x32x16_bf16 v[64:79], v[104:107], v[96:99], v[64:79]
	v_add_f32_e32 v96, 0, v238
	v_add_f32_e32 v96, v239, v96
	v_add_f32_e32 v96, v240, v96
	v_add_f32_e32 v96, v246, v96
	v_add_f32_e32 v96, v247, v96
	v_add_f32_e32 v96, v248, v96
	v_add_f32_e32 v96, v249, v96
	v_add_f32_e32 v96, v250, v96
	v_add_f32_e32 v96, v251, v96
	v_add_f32_e32 v96, v252, v96
	v_add_f32_e32 v96, v253, v96
	v_add_f32_e32 v96, v241, v96
	v_exp_f32_e32 v106, v156
	v_add_f32_e32 v96, v243, v96
	v_exp_f32_e32 v107, v157
	v_add_f32_e32 v96, v244, v96
	v_add_f32_e32 v96, v245, v96
	v_add_f32_e32 v96, v193, v96
	v_add_f32_e32 v96, v106, v96
	v_add_f32_e32 v96, v107, v96
	v_add_f32_e32 v96, v108, v96
	v_add_f32_e32 v96, v109, v96
	v_add_f32_e32 v96, v110, v96
	v_add_f32_e32 v96, v111, v96
	v_add_f32_e32 v96, v112, v96
	v_add_f32_e32 v96, v113, v96
	v_add_f32_e32 v96, v114, v96
	v_add_f32_e32 v96, v115, v96
	v_add_f32_e32 v96, v116, v96
	v_add_f32_e32 v96, v117, v96
	v_add_f32_e32 v96, v118, v96
	v_add_f32_e32 v96, v119, v96
	v_add_f32_e32 v96, v120, v96
	v_add_f32_e32 v96, v121, v96
	v_mov_b32_e32 v97, v96
	v_cvt_pk_bf16_f32 v98, v238, v239
	v_cvt_pk_bf16_f32 v99, v240, v246
	v_cvt_pk_bf16_f32 v100, v247, v248
	v_cvt_pk_bf16_f32 v101, v249, v250
	s_nop 1
	v_permlane32_swap_b32_e32 v96, v97
	v_permlane32_swap_b32_e32 v98, v100
	v_permlane32_swap_b32_e32 v99, v101
	v_cvt_pk_bf16_f32 v102, v251, v252
	v_cvt_pk_bf16_f32 v103, v253, v241
	v_cvt_pk_bf16_f32 v104, v243, v244
	v_cvt_pk_bf16_f32 v105, v245, v193
	v_cvt_pk_bf16_f32 v106, v106, v107
	v_cvt_pk_bf16_f32 v107, v108, v109
	v_cvt_pk_bf16_f32 v108, v110, v111
	v_cvt_pk_bf16_f32 v109, v112, v113
	v_cvt_pk_bf16_f32 v110, v114, v115
	v_cvt_pk_bf16_f32 v111, v116, v117
	v_cvt_pk_bf16_f32 v112, v118, v119
	v_cvt_pk_bf16_f32 v113, v120, v121
	s_nop 0
	v_permlane32_swap_b32_e32 v102, v104
	v_permlane32_swap_b32_e32 v103, v105
	v_permlane32_swap_b32_e32 v106, v108
	v_permlane32_swap_b32_e32 v107, v109
	v_permlane32_swap_b32_e32 v110, v112
	v_permlane32_swap_b32_e32 v111, v113
	ds_read_b64_tr_b16 v[114:115], v182 offset:0
	ds_read_b64_tr_b16 v[116:117], v182 offset:0x800
	ds_read_b64_tr_b16 v[118:119], v182 offset:0x1000
	ds_read_b64_tr_b16 v[120:121], v182 offset:0x1800
	ds_read_b64_tr_b16 v[122:123], v182 offset:0x2000
	ds_read_b64_tr_b16 v[124:125], v182 offset:0x2800
	ds_read_b64_tr_b16 v[126:127], v182 offset:0x3000
	ds_read_b64_tr_b16 v[128:129], v182 offset:0x3800
	s_waitcnt lgkmcnt(0)
	s_nop 0
	v_mfma_f32_32x32x16_bf16 v[0:15], v[98:101], v[114:117], v[0:15]
	ds_read_b64_tr_b16 v[114:115], v182 offset:0x200
	ds_read_b64_tr_b16 v[116:117], v182 offset:0xa00
	v_mfma_f32_32x32x16_bf16 v[0:15], v[102:105], v[118:121], v[0:15]
	ds_read_b64_tr_b16 v[118:119], v182 offset:0x1200
	ds_read_b64_tr_b16 v[120:121], v182 offset:0x1a00
	v_mfma_f32_32x32x16_bf16 v[0:15], v[106:109], v[122:125], v[0:15]
	ds_read_b64_tr_b16 v[122:123], v182 offset:0x2200
	ds_read_b64_tr_b16 v[124:125], v182 offset:0x2a00
	v_mfma_f32_32x32x16_bf16 v[0:15], v[110:113], v[126:129], v[0:15]
	ds_read_b64_tr_b16 v[126:127], v182 offset:0x3200
	ds_read_b64_tr_b16 v[128:129], v182 offset:0x3a00
	s_waitcnt lgkmcnt(0)
	v_mfma_f32_32x32x16_bf16 v[48:63], v[98:101], v[114:117], v[48:63]
	ds_read_b64_tr_b16 v[114:115], v182 offset:0x400
	ds_read_b64_tr_b16 v[116:117], v182 offset:0xc00
	v_mfma_f32_32x32x16_bf16 v[48:63], v[102:105], v[118:121], v[48:63]
	ds_read_b64_tr_b16 v[118:119], v182 offset:0x1400
	ds_read_b64_tr_b16 v[120:121], v182 offset:0x1c00
	v_mfma_f32_32x32x16_bf16 v[48:63], v[106:109], v[122:125], v[48:63]
	ds_read_b64_tr_b16 v[122:123], v182 offset:0x2400
	ds_read_b64_tr_b16 v[124:125], v182 offset:0x2c00
	v_mfma_f32_32x32x16_bf16 v[48:63], v[110:113], v[126:129], v[48:63]
	ds_read_b64_tr_b16 v[126:127], v182 offset:0x3400
	ds_read_b64_tr_b16 v[128:129], v182 offset:0x3c00
	s_waitcnt lgkmcnt(0)
	v_mfma_f32_32x32x16_bf16 v[32:47], v[98:101], v[114:117], v[32:47]
	ds_read_b64_tr_b16 v[114:115], v182 offset:0x600
	ds_read_b64_tr_b16 v[116:117], v182 offset:0xe00
	v_mfma_f32_32x32x16_bf16 v[32:47], v[102:105], v[118:121], v[32:47]
	ds_read_b64_tr_b16 v[118:119], v182 offset:0x1600
	ds_read_b64_tr_b16 v[120:121], v182 offset:0x1e00
	v_mfma_f32_32x32x16_bf16 v[32:47], v[106:109], v[122:125], v[32:47]
	ds_read_b64_tr_b16 v[122:123], v182 offset:0x2600
	ds_read_b64_tr_b16 v[124:125], v182 offset:0x2e00
	v_mfma_f32_32x32x16_bf16 v[32:47], v[110:113], v[126:129], v[32:47]
	ds_read_b64_tr_b16 v[126:127], v182 offset:0x3600
	ds_read_b64_tr_b16 v[128:129], v182 offset:0x3e00
	s_waitcnt lgkmcnt(0)
	v_mfma_f32_32x32x16_bf16 v[16:31], v[98:101], v[114:117], v[16:31]
	v_max_f32_e32 v98, v81, v81
	v_max_f32_e32 v99, v80, v80
	v_max_f32_e32 v98, v99, v98
	v_max3_f32 v98, v98, v82, v83
	v_max3_f32 v98, v98, v84, v85
	v_max3_f32 v98, v98, v86, v87
	v_max3_f32 v98, v98, v88, v89
	v_max3_f32 v98, v98, v90, v91
	v_max3_f32 v98, v98, v92, v93
	v_mfma_f32_32x32x16_bf16 v[16:31], v[102:105], v[118:121], v[16:31]
	v_max3_f32 v98, v98, v94, v95
	v_max3_f32 v98, v98, v64, v65
	v_max3_f32 v98, v98, v66, v67
	v_max3_f32 v98, v98, v68, v69
	v_max3_f32 v98, v98, v70, v71
	v_max3_f32 v98, v98, v72, v73
	v_max3_f32 v98, v98, v74, v75
	v_max3_f32 v98, v98, v76, v77
	v_mfma_f32_32x32x16_bf16 v[16:31], v[106:109], v[122:125], v[16:31]
	v_max3_f32 v98, v98, v78, v79
	v_mov_b32_e32 v99, v98
	s_nop 1
	v_permlane32_swap_b32_e32 v98, v99
	v_max_f32_e32 v99, v99, v99
	v_max_f32_e32 v98, v98, v98
	v_max_f32_e32 v98, v98, v99
	v_sub_f32_e32 v99, v98, v164
	v_cmp_ge_f32_e32 vcc, s85, v99
	v_max_f32_e32 v99, v164, v164
	v_max_f32_e32 v99, v99, v98
	v_mfma_f32_32x32x16_bf16 v[16:31], v[110:113], v[126:129], v[16:31]
	v_sub_f32_e32 v98, v164, v99
	v_mul_f32_e32 v98, 0x3e0293ee, v98
	v_exp_f32_e32 v98, v98
	s_cmp_eq_u64 vcc, exec
	s_cselect_b64 s[42:43], -1, 0
	v_cndmask_b32_e64 v98, v98, 1.0, s[42:43]
	v_cmp_gt_f32_e32 vcc, 1.0, v98
	s_barrier
	s_cbranch_vccz .LBB0_742
	s_and_saveexec_b64 s[2:3], s[40:41]
	ds_write_b32 v185, v98 offset:128
	s_or_b64 exec, exec, s[2:3]
	s_waitcnt lgkmcnt(0)
	v_add_u32_e32 v112, v177, v194
	ds_read_b128 v[100:103], v112 offset:224
	ds_read_b128 v[104:107], v112 offset:192
	ds_read_b128 v[108:111], v112 offset:160
	ds_read_b128 v[112:115], v112 offset:128
	s_waitcnt lgkmcnt(3)
	v_pk_mul_f32 v[12:13], v[12:13], v[100:101]
	s_waitcnt lgkmcnt(2)
	v_pk_mul_f32 v[8:9], v[8:9], v[104:105]
	s_waitcnt lgkmcnt(1)
	v_pk_mul_f32 v[4:5], v[4:5], v[108:109]
	v_pk_mul_f32 v[14:15], v[14:15], v[102:103]
	v_pk_mul_f32 v[10:11], v[10:11], v[106:107]
	v_pk_mul_f32 v[6:7], v[6:7], v[110:111]
	s_waitcnt lgkmcnt(0)
	v_pk_mul_f32 v[2:3], v[2:3], v[114:115]
	v_pk_mul_f32 v[0:1], v[0:1], v[112:113]
	v_pk_mul_f32 v[60:61], v[60:61], v[100:101]
	v_pk_mul_f32 v[56:57], v[56:57], v[104:105]
	v_pk_mul_f32 v[52:53], v[52:53], v[108:109]
	v_pk_mul_f32 v[62:63], v[62:63], v[102:103]
	v_pk_mul_f32 v[58:59], v[58:59], v[106:107]
	v_pk_mul_f32 v[54:55], v[54:55], v[110:111]
	v_pk_mul_f32 v[50:51], v[50:51], v[114:115]
	v_pk_mul_f32 v[48:49], v[48:49], v[112:113]
	v_pk_mul_f32 v[44:45], v[44:45], v[100:101]
	v_pk_mul_f32 v[40:41], v[40:41], v[104:105]
	v_pk_mul_f32 v[36:37], v[36:37], v[108:109]
	v_pk_mul_f32 v[46:47], v[46:47], v[102:103]
	v_pk_mul_f32 v[42:43], v[42:43], v[106:107]
	v_pk_mul_f32 v[38:39], v[38:39], v[110:111]
	v_pk_mul_f32 v[34:35], v[34:35], v[114:115]
	v_pk_mul_f32 v[32:33], v[32:33], v[112:113]
	v_pk_mul_f32 v[28:29], v[28:29], v[100:101]
	v_pk_mul_f32 v[24:25], v[24:25], v[104:105]
	v_pk_mul_f32 v[20:21], v[20:21], v[108:109]
	v_pk_mul_f32 v[30:31], v[30:31], v[102:103]
	v_pk_mul_f32 v[26:27], v[26:27], v[106:107]
	v_pk_mul_f32 v[22:23], v[22:23], v[110:111]
	v_pk_mul_f32 v[18:19], v[18:19], v[114:115]
	v_pk_mul_f32 v[16:17], v[16:17], v[112:113]
